# s5_scan item: issue both carry-load pairs before first wait (one memory round trip less per scan item), on top of v43
# baseline (speedup 1.0000x reference)
; __device__ __forceinline__ int otid() { int t = threadIdx.x; asm volatile("" : "+v"(t)); return t; }
; __device__ void s5_scan(const Params& p) {
;     const int lane = otid() & 63;
;     float* Xloc = (float*)(p.ws + WS_XLOC);
;     const float* a16 = (const float*)(p.ws + WS_A16);
;     for (int ci = p.bid; ci < 256; ci += p.nblk) {
;         const int b = ci >> 5, g = ci & 31;
;         const float ar = a16[(g * 64 + lane) * 2], ai = a16[(g * 64 + lane) * 2 + 1];
;         float* base = Xloc + ((size_t)(b * 258) * 32 + g) * 128 + lane;
;         float sr = 0.f, si = 0.f;
;         for (int c0 = 0; c0 < 258; c0 += 43) { float xr[43], xi[43];
; #pragma unroll
;             for (int j = 0; j < 43; ++j) { xr[j] = base[(size_t)(c0 + j) * 4096]; xi[j] = base[(size_t)(c0 + j) * 4096 + 64]; }
; #pragma unroll
;             for (int j = 0; j < 43; ++j) { if (!p.dry) { base[(size_t)(c0 + j) * 4096] = sr; base[(size_t)(c0 + j) * 4096 + 64] = si; }
;                 const float nr = ar * sr - ai * si + xr[j], ni = ar * si + ai * sr + xi[j]; sr = nr; si = ni; } }
;     }
; }
.LBB0_407:
	v_ashrrev_i32_e32 v9, 31, v2
	v_mov_b32_e32 v8, v2
	v_ashrrev_i32_e32 v11, 31, v3
	v_mov_b32_e32 v10, v3
	v_lshl_add_u64 v[8:9], s[40:41], 0, v[8:9]
	v_lshl_add_u64 v[10:11], s[58:59], 0, v[10:11]
	v_lshlrev_b64 v[8:9], 2, v[8:9]
	v_lshl_add_u64 v[12:13], s[70:71], 0, v[8:9]
	v_lshlrev_b64 v[10:11], 2, v[10:11]
	v_lshl_add_u64 v[14:15], s[70:71], 0, v[10:11]
	global_load_dword v7, v[12:13], off
	s_nop 0
	global_load_dword v12, v[14:15], off
	v_lshl_add_u64 v[8:9], s[72:73], 0, v[8:9]
	v_lshl_add_u64 v[10:11], s[72:73], 0, v[10:11]
	v_add_u32_e32 v5, -2, v5
	v_cmp_eq_u32_e32 vcc, 0, v5
	v_add_u32_e32 v3, 0x400, v3
	v_add_u32_e32 v2, 0x400, v2
	s_or_b64 s[60:61], vcc, s[60:61]
	global_load_dword v13, v[8:9], off
	s_nop 0
	global_load_dword v14, v[10:11], off
	v_add_u32_e32 v9, 0x1000, v6
	s_waitcnt vmcnt(2)
	ds_write2st64_b32 v6, v7, v12 offset1:8
	s_waitcnt vmcnt(0)
	ds_write2st64_b32 v6, v13, v14 offset0:16 offset1:24
	v_mov_b32_e32 v6, v9
	s_andn2_b64 exec, exec, s[60:61]
	s_cbranch_execnz .LBB0_407
	s_or_b64 exec, exec, s[60:61]
	v_cmp_ne_u32_e32 vcc, v0, v4
	v_lshl_add_u32 v2, v4, 9, v34
	s_orn2_b64 s[58:59], vcc, exec
